# compress-MLP tile prologue: 16 bias partial loads batched instead of one waited load at a time (same add order)
# speedup vs baseline: 1.0000x; 1.0000x over previous
; __global__ void __launch_bounds__(256, LB2) mega(Params p, int ph_lo, int ph_hi) {
;     ...
;         if (t < n_c1) {
;           const int which = t >> 4, tm = (t >> 1) & 7, tn = t & 1;
;           const int m0 = tm * 128, n0 = tn * 128;
;           __syncthreads();
;           if (tid < 128) {
;             const float* CB = (const float*)(ws + WS_CMPB) + which * 16 * 256 + n0 + tid;
;             float b = 0.f;
;             for (int q = 0; q < 16; ++q) b += CB[q * 256];
;             rsx[tid] = b;
;           }
.LBB0_427:
	s_andn2_b64 vcc, exec, s[0:1]
	s_cbranch_vccnz .LBB0_365
	s_lshl_b32 s0, s60, 7
	s_and_b32 s64, s0, 0x80
	v_mov_b64_e32 v[130:131], s[64:65]
	s_waitcnt lgkmcnt(0)
	s_barrier
	s_and_saveexec_b64 s[0:1], s[10:11]
	s_xor_b64 s[0:1], exec, s[0:1]
	v_mov_b64_e32 v[130:131], s[64:65]
	s_andn2_saveexec_b64 s[0:1], s[0:1]
	s_cbranch_execz .LBB0_432
	s_lshl_b32 s6, s60, 8
	s_and_b32 s6, s6, 0xfffff000
	s_ashr_i32 s7, s6, 31
	s_lshl_b64 s[6:7], s[6:7], 2
	s_add_u32 s6, s44, s6
	s_addc_u32 s7, s45, s7
	s_lshl_b32 s12, s64, 2
	s_add_u32 s6, s6, s12
	s_addc_u32 s7, s7, 0
	v_lshl_add_u64 v[2:3], v[192:193], 2, s[6:7]
	s_movk_i32 s6, 0x1000
	v_add_co_u32_e32 v4, vcc, s6, v2
	s_nop 1
	v_addc_co_u32_e32 v5, vcc, 0, v3, vcc
	v_add_co_u32_e32 v6, vcc, s95, v2
	s_nop 1
	v_addc_co_u32_e32 v7, vcc, 0, v3, vcc
	global_load_dword v16, v[2:3], off
	global_load_dword v17, v[2:3], off offset:1024
	global_load_dword v18, v[2:3], off offset:2048
	global_load_dword v19, v[2:3], off offset:3072
	global_load_dword v20, v[4:5], off
	global_load_dword v21, v[4:5], off offset:1024
	global_load_dword v22, v[4:5], off offset:2048
	global_load_dword v23, v[4:5], off offset:3072
	global_load_dword v24, v[6:7], off
	global_load_dword v25, v[6:7], off offset:1024
	global_load_dword v26, v[6:7], off offset:2048
	global_load_dword v27, v[6:7], off offset:3072
	v_add_co_u32_e32 v4, vcc, s95, v4
	s_nop 1
	v_addc_co_u32_e32 v5, vcc, 0, v5, vcc
	global_load_dword v28, v[4:5], off
	global_load_dword v29, v[4:5], off offset:1024
	global_load_dword v30, v[4:5], off offset:2048
	global_load_dword v31, v[4:5], off offset:3072
	s_waitcnt vmcnt(0)
	v_add_f32_e32 v0, 0, v16
	v_add_f32_e32 v0, v0, v17
	v_add_f32_e32 v0, v0, v18
	v_add_f32_e32 v0, v0, v19
	v_add_f32_e32 v0, v0, v20
	v_add_f32_e32 v0, v0, v21
	v_add_f32_e32 v0, v0, v22
	v_add_f32_e32 v0, v0, v23
	v_add_f32_e32 v0, v0, v24
	v_add_f32_e32 v0, v0, v25
	v_add_f32_e32 v0, v0, v26
	v_add_f32_e32 v0, v0, v27
	v_add_f32_e32 v0, v0, v28
	v_add_f32_e32 v0, v0, v29
	v_add_f32_e32 v0, v0, v30
	v_add_f32_e32 v0, v0, v31
	ds_write_b32 v169, v0
